# v24: v22 + GLA G2 chunk scan software-pipelined by hand (loads of chunk k+8 issued as chunk k is consumed, counted vmcnt)
# speedup vs baseline: 1.0585x; 1.0022x over previous
.LBB0_141:
	s_mov_b64 s[10:11], 0x10000
	s_mov_b64 s[12:13], 0x200
	s_mov_b32 vcc_lo, 0xfff90000
	s_mov_b32 vcc_hi, -1
	v_lshl_add_u64 v[96:97], v[94:95], 0, vcc
	v_lshl_add_u64 v[98:99], v[94:95], 0, s[10:11]
	s_mov_b64 vcc, 0x1000
	v_lshl_add_u64 v[102:103], v[92:93], 0, vcc
	v_lshl_add_u64 v[108:109], v[96:97], 0, 0
	global_load_dwordx4 v[0:3], v[108:109], off
	global_load_dwordx4 v[4:7], v[92:93], off
	global_load_dwordx4 v[8:11], v[92:93], off offset:32
	v_lshl_add_u64 v[108:109], v[108:109], 0, s[10:11]
	global_load_dwordx4 v[12:15], v[108:109], off
	global_load_dwordx4 v[16:19], v[92:93], off offset:512
	global_load_dwordx4 v[20:23], v[92:93], off offset:544
	v_lshl_add_u64 v[108:109], v[108:109], 0, s[10:11]
	global_load_dwordx4 v[24:27], v[108:109], off
	global_load_dwordx4 v[28:31], v[92:93], off offset:1024
	global_load_dwordx4 v[32:35], v[92:93], off offset:1056
	v_lshl_add_u64 v[108:109], v[108:109], 0, s[10:11]
	global_load_dwordx4 v[36:39], v[108:109], off
	global_load_dwordx4 v[40:43], v[92:93], off offset:1536
	global_load_dwordx4 v[44:47], v[92:93], off offset:1568
	v_lshl_add_u64 v[108:109], v[108:109], 0, s[10:11]
	global_load_dwordx4 v[48:51], v[108:109], off
	global_load_dwordx4 v[52:55], v[92:93], off offset:2048
	global_load_dwordx4 v[56:59], v[92:93], off offset:2080
	v_lshl_add_u64 v[108:109], v[108:109], 0, s[10:11]
	global_load_dwordx4 v[60:63], v[108:109], off
	global_load_dwordx4 v[64:67], v[92:93], off offset:2560
	global_load_dwordx4 v[68:71], v[92:93], off offset:2592
	v_lshl_add_u64 v[108:109], v[108:109], 0, s[10:11]
	global_load_dwordx4 v[72:75], v[108:109], off
	global_load_dwordx4 v[76:79], v[92:93], off offset:3072
	global_load_dwordx4 v[80:83], v[92:93], off offset:3104
	v_lshl_add_u64 v[108:109], v[108:109], 0, s[10:11]
	global_load_dwordx4 v[84:87], v[108:109], off
	global_load_dwordx4 v[88:91], v[92:93], off offset:3584
	global_load_dwordx4 v[118:121], v[92:93], off offset:3616
	s_waitcnt vmcnt(21)
	v_cvt_pk_bf16_f32 v124, v100, v101
	v_cvt_pk_bf16_f32 v125, v104, v105
	v_cvt_pk_bf16_f32 v126, v106, v107
	v_cvt_pk_bf16_f32 v127, v110, v111
	global_store_dwordx4 v[96:97], v[124:127], off
	v_lshlrev_b32_e32 v108, 16, v0
	v_and_b32_e32 v109, 0xffff0000, v0
	v_lshlrev_b32_e32 v112, 16, v1
	v_and_b32_e32 v113, 0xffff0000, v1
	v_lshlrev_b32_e32 v114, 16, v2
	v_and_b32_e32 v115, 0xffff0000, v2
	v_lshlrev_b32_e32 v122, 16, v3
	v_and_b32_e32 v123, 0xffff0000, v3
	v_pk_fma_f32 v[100:101], v[100:101], v[4:5], v[108:109]
	v_pk_fma_f32 v[104:105], v[104:105], v[6:7], v[112:113]
	v_pk_fma_f32 v[106:107], v[106:107], v[8:9], v[114:115]
	v_pk_fma_f32 v[110:111], v[110:111], v[10:11], v[122:123]
	global_load_dwordx4 v[0:3], v[98:99], off
	global_load_dwordx4 v[4:7], v[102:103], off
	global_load_dwordx4 v[8:11], v[102:103], off offset:32
	v_lshl_add_u64 v[98:99], v[98:99], 0, s[10:11]
	v_lshl_add_u64 v[102:103], v[102:103], 0, s[12:13]
	v_lshl_add_u64 v[96:97], v[96:97], 0, s[10:11]
	s_waitcnt vmcnt(22)
	v_cvt_pk_bf16_f32 v124, v100, v101
	v_cvt_pk_bf16_f32 v125, v104, v105
	v_cvt_pk_bf16_f32 v126, v106, v107
	v_cvt_pk_bf16_f32 v127, v110, v111
	global_store_dwordx4 v[96:97], v[124:127], off
	v_lshlrev_b32_e32 v108, 16, v12
	v_and_b32_e32 v109, 0xffff0000, v12
	v_lshlrev_b32_e32 v112, 16, v13
	v_and_b32_e32 v113, 0xffff0000, v13
	v_lshlrev_b32_e32 v114, 16, v14
	v_and_b32_e32 v115, 0xffff0000, v14
	v_lshlrev_b32_e32 v122, 16, v15
	v_and_b32_e32 v123, 0xffff0000, v15
	v_pk_fma_f32 v[100:101], v[100:101], v[16:17], v[108:109]
	v_pk_fma_f32 v[104:105], v[104:105], v[18:19], v[112:113]
	v_pk_fma_f32 v[106:107], v[106:107], v[20:21], v[114:115]
	v_pk_fma_f32 v[110:111], v[110:111], v[22:23], v[122:123]
	global_load_dwordx4 v[12:15], v[98:99], off
	global_load_dwordx4 v[16:19], v[102:103], off
	global_load_dwordx4 v[20:23], v[102:103], off offset:32
	v_lshl_add_u64 v[98:99], v[98:99], 0, s[10:11]
	v_lshl_add_u64 v[102:103], v[102:103], 0, s[12:13]
	v_lshl_add_u64 v[96:97], v[96:97], 0, s[10:11]
	s_waitcnt vmcnt(23)
	v_cvt_pk_bf16_f32 v124, v100, v101
	v_cvt_pk_bf16_f32 v125, v104, v105
	v_cvt_pk_bf16_f32 v126, v106, v107
	v_cvt_pk_bf16_f32 v127, v110, v111
	global_store_dwordx4 v[96:97], v[124:127], off
	v_lshlrev_b32_e32 v108, 16, v24
	v_and_b32_e32 v109, 0xffff0000, v24
	v_lshlrev_b32_e32 v112, 16, v25
	v_and_b32_e32 v113, 0xffff0000, v25
	v_lshlrev_b32_e32 v114, 16, v26
	v_and_b32_e32 v115, 0xffff0000, v26
	v_lshlrev_b32_e32 v122, 16, v27
	v_and_b32_e32 v123, 0xffff0000, v27
	v_pk_fma_f32 v[100:101], v[100:101], v[28:29], v[108:109]
	v_pk_fma_f32 v[104:105], v[104:105], v[30:31], v[112:113]
	v_pk_fma_f32 v[106:107], v[106:107], v[32:33], v[114:115]
	v_pk_fma_f32 v[110:111], v[110:111], v[34:35], v[122:123]
	global_load_dwordx4 v[24:27], v[98:99], off
	global_load_dwordx4 v[28:31], v[102:103], off
	global_load_dwordx4 v[32:35], v[102:103], off offset:32
	v_lshl_add_u64 v[98:99], v[98:99], 0, s[10:11]
	v_lshl_add_u64 v[102:103], v[102:103], 0, s[12:13]
	v_lshl_add_u64 v[96:97], v[96:97], 0, s[10:11]
	s_waitcnt vmcnt(24)
	v_cvt_pk_bf16_f32 v124, v100, v101
	v_cvt_pk_bf16_f32 v125, v104, v105
	v_cvt_pk_bf16_f32 v126, v106, v107
	v_cvt_pk_bf16_f32 v127, v110, v111
	global_store_dwordx4 v[96:97], v[124:127], off
	v_lshlrev_b32_e32 v108, 16, v36
	v_and_b32_e32 v109, 0xffff0000, v36
	v_lshlrev_b32_e32 v112, 16, v37
	v_and_b32_e32 v113, 0xffff0000, v37
	v_lshlrev_b32_e32 v114, 16, v38
	v_and_b32_e32 v115, 0xffff0000, v38
	v_lshlrev_b32_e32 v122, 16, v39
	v_and_b32_e32 v123, 0xffff0000, v39
	v_pk_fma_f32 v[100:101], v[100:101], v[40:41], v[108:109]
	v_pk_fma_f32 v[104:105], v[104:105], v[42:43], v[112:113]
	v_pk_fma_f32 v[106:107], v[106:107], v[44:45], v[114:115]
	v_pk_fma_f32 v[110:111], v[110:111], v[46:47], v[122:123]
	global_load_dwordx4 v[36:39], v[98:99], off
	global_load_dwordx4 v[40:43], v[102:103], off
	global_load_dwordx4 v[44:47], v[102:103], off offset:32
	v_lshl_add_u64 v[98:99], v[98:99], 0, s[10:11]
	v_lshl_add_u64 v[102:103], v[102:103], 0, s[12:13]
	v_lshl_add_u64 v[96:97], v[96:97], 0, s[10:11]
	s_waitcnt vmcnt(25)
	v_cvt_pk_bf16_f32 v124, v100, v101
	v_cvt_pk_bf16_f32 v125, v104, v105
	v_cvt_pk_bf16_f32 v126, v106, v107
	v_cvt_pk_bf16_f32 v127, v110, v111
	global_store_dwordx4 v[96:97], v[124:127], off
	v_lshlrev_b32_e32 v108, 16, v48
	v_and_b32_e32 v109, 0xffff0000, v48
	v_lshlrev_b32_e32 v112, 16, v49
	v_and_b32_e32 v113, 0xffff0000, v49
	v_lshlrev_b32_e32 v114, 16, v50
	v_and_b32_e32 v115, 0xffff0000, v50
	v_lshlrev_b32_e32 v122, 16, v51
	v_and_b32_e32 v123, 0xffff0000, v51
	v_pk_fma_f32 v[100:101], v[100:101], v[52:53], v[108:109]
	v_pk_fma_f32 v[104:105], v[104:105], v[54:55], v[112:113]
	v_pk_fma_f32 v[106:107], v[106:107], v[56:57], v[114:115]
	v_pk_fma_f32 v[110:111], v[110:111], v[58:59], v[122:123]
	global_load_dwordx4 v[48:51], v[98:99], off
	global_load_dwordx4 v[52:55], v[102:103], off
	global_load_dwordx4 v[56:59], v[102:103], off offset:32
	v_lshl_add_u64 v[98:99], v[98:99], 0, s[10:11]
	v_lshl_add_u64 v[102:103], v[102:103], 0, s[12:13]
	v_lshl_add_u64 v[96:97], v[96:97], 0, s[10:11]
	s_waitcnt vmcnt(26)
	v_cvt_pk_bf16_f32 v124, v100, v101
	v_cvt_pk_bf16_f32 v125, v104, v105
	v_cvt_pk_bf16_f32 v126, v106, v107
	v_cvt_pk_bf16_f32 v127, v110, v111
	global_store_dwordx4 v[96:97], v[124:127], off
	v_lshlrev_b32_e32 v108, 16, v60
	v_and_b32_e32 v109, 0xffff0000, v60
	v_lshlrev_b32_e32 v112, 16, v61
	v_and_b32_e32 v113, 0xffff0000, v61
	v_lshlrev_b32_e32 v114, 16, v62
	v_and_b32_e32 v115, 0xffff0000, v62
	v_lshlrev_b32_e32 v122, 16, v63
	v_and_b32_e32 v123, 0xffff0000, v63
	v_pk_fma_f32 v[100:101], v[100:101], v[64:65], v[108:109]
	v_pk_fma_f32 v[104:105], v[104:105], v[66:67], v[112:113]
	v_pk_fma_f32 v[106:107], v[106:107], v[68:69], v[114:115]
	v_pk_fma_f32 v[110:111], v[110:111], v[70:71], v[122:123]
	global_load_dwordx4 v[60:63], v[98:99], off
	global_load_dwordx4 v[64:67], v[102:103], off
	global_load_dwordx4 v[68:71], v[102:103], off offset:32
	v_lshl_add_u64 v[98:99], v[98:99], 0, s[10:11]
	v_lshl_add_u64 v[102:103], v[102:103], 0, s[12:13]
	v_lshl_add_u64 v[96:97], v[96:97], 0, s[10:11]
	s_waitcnt vmcnt(27)
	v_cvt_pk_bf16_f32 v124, v100, v101
	v_cvt_pk_bf16_f32 v125, v104, v105
	v_cvt_pk_bf16_f32 v126, v106, v107
	v_cvt_pk_bf16_f32 v127, v110, v111
	global_store_dwordx4 v[96:97], v[124:127], off
	v_lshlrev_b32_e32 v108, 16, v72
	v_and_b32_e32 v109, 0xffff0000, v72
	v_lshlrev_b32_e32 v112, 16, v73
	v_and_b32_e32 v113, 0xffff0000, v73
	v_lshlrev_b32_e32 v114, 16, v74
	v_and_b32_e32 v115, 0xffff0000, v74
	v_lshlrev_b32_e32 v122, 16, v75
	v_and_b32_e32 v123, 0xffff0000, v75
	v_pk_fma_f32 v[100:101], v[100:101], v[76:77], v[108:109]
	v_pk_fma_f32 v[104:105], v[104:105], v[78:79], v[112:113]
	v_pk_fma_f32 v[106:107], v[106:107], v[80:81], v[114:115]
	v_pk_fma_f32 v[110:111], v[110:111], v[82:83], v[122:123]
	global_load_dwordx4 v[72:75], v[98:99], off
	global_load_dwordx4 v[76:79], v[102:103], off
	global_load_dwordx4 v[80:83], v[102:103], off offset:32
	v_lshl_add_u64 v[98:99], v[98:99], 0, s[10:11]
	v_lshl_add_u64 v[102:103], v[102:103], 0, s[12:13]
	v_lshl_add_u64 v[96:97], v[96:97], 0, s[10:11]
	s_waitcnt vmcnt(28)
	v_cvt_pk_bf16_f32 v124, v100, v101
	v_cvt_pk_bf16_f32 v125, v104, v105
	v_cvt_pk_bf16_f32 v126, v106, v107
	v_cvt_pk_bf16_f32 v127, v110, v111
	global_store_dwordx4 v[96:97], v[124:127], off
	v_lshlrev_b32_e32 v108, 16, v84
	v_and_b32_e32 v109, 0xffff0000, v84
	v_lshlrev_b32_e32 v112, 16, v85
	v_and_b32_e32 v113, 0xffff0000, v85
	v_lshlrev_b32_e32 v114, 16, v86
	v_and_b32_e32 v115, 0xffff0000, v86
	v_lshlrev_b32_e32 v122, 16, v87
	v_and_b32_e32 v123, 0xffff0000, v87
	v_pk_fma_f32 v[100:101], v[100:101], v[88:89], v[108:109]
	v_pk_fma_f32 v[104:105], v[104:105], v[90:91], v[112:113]
	v_pk_fma_f32 v[106:107], v[106:107], v[118:119], v[114:115]
	v_pk_fma_f32 v[110:111], v[110:111], v[120:121], v[122:123]
	global_load_dwordx4 v[84:87], v[98:99], off
	global_load_dwordx4 v[88:91], v[102:103], off
	global_load_dwordx4 v[118:121], v[102:103], off offset:32
	v_lshl_add_u64 v[98:99], v[98:99], 0, s[10:11]
	v_lshl_add_u64 v[102:103], v[102:103], 0, s[12:13]
	v_lshl_add_u64 v[96:97], v[96:97], 0, s[10:11]
	s_mov_b32 s5, 1
.Lg2_loop:
	s_waitcnt vmcnt(28)
	v_cvt_pk_bf16_f32 v124, v100, v101
	v_cvt_pk_bf16_f32 v125, v104, v105
	v_cvt_pk_bf16_f32 v126, v106, v107
	v_cvt_pk_bf16_f32 v127, v110, v111
	global_store_dwordx4 v[96:97], v[124:127], off
	v_lshlrev_b32_e32 v108, 16, v0
	v_and_b32_e32 v109, 0xffff0000, v0
	v_lshlrev_b32_e32 v112, 16, v1
	v_and_b32_e32 v113, 0xffff0000, v1
	v_lshlrev_b32_e32 v114, 16, v2
	v_and_b32_e32 v115, 0xffff0000, v2
	v_lshlrev_b32_e32 v122, 16, v3
	v_and_b32_e32 v123, 0xffff0000, v3
	v_pk_fma_f32 v[100:101], v[100:101], v[4:5], v[108:109]
	v_pk_fma_f32 v[104:105], v[104:105], v[6:7], v[112:113]
	v_pk_fma_f32 v[106:107], v[106:107], v[8:9], v[114:115]
	v_pk_fma_f32 v[110:111], v[110:111], v[10:11], v[122:123]
	global_load_dwordx4 v[0:3], v[98:99], off
	global_load_dwordx4 v[4:7], v[102:103], off
	global_load_dwordx4 v[8:11], v[102:103], off offset:32
	v_lshl_add_u64 v[98:99], v[98:99], 0, s[10:11]
	v_lshl_add_u64 v[102:103], v[102:103], 0, s[12:13]
	v_lshl_add_u64 v[96:97], v[96:97], 0, s[10:11]
	s_waitcnt vmcnt(28)
	v_cvt_pk_bf16_f32 v124, v100, v101
	v_cvt_pk_bf16_f32 v125, v104, v105
	v_cvt_pk_bf16_f32 v126, v106, v107
	v_cvt_pk_bf16_f32 v127, v110, v111
	global_store_dwordx4 v[96:97], v[124:127], off
	v_lshlrev_b32_e32 v108, 16, v12
	v_and_b32_e32 v109, 0xffff0000, v12
	v_lshlrev_b32_e32 v112, 16, v13
	v_and_b32_e32 v113, 0xffff0000, v13
	v_lshlrev_b32_e32 v114, 16, v14
	v_and_b32_e32 v115, 0xffff0000, v14
	v_lshlrev_b32_e32 v122, 16, v15
	v_and_b32_e32 v123, 0xffff0000, v15
	v_pk_fma_f32 v[100:101], v[100:101], v[16:17], v[108:109]
	v_pk_fma_f32 v[104:105], v[104:105], v[18:19], v[112:113]
	v_pk_fma_f32 v[106:107], v[106:107], v[20:21], v[114:115]
	v_pk_fma_f32 v[110:111], v[110:111], v[22:23], v[122:123]
	global_load_dwordx4 v[12:15], v[98:99], off
	global_load_dwordx4 v[16:19], v[102:103], off
	global_load_dwordx4 v[20:23], v[102:103], off offset:32
	v_lshl_add_u64 v[98:99], v[98:99], 0, s[10:11]
	v_lshl_add_u64 v[102:103], v[102:103], 0, s[12:13]
	v_lshl_add_u64 v[96:97], v[96:97], 0, s[10:11]
	s_waitcnt vmcnt(28)
	v_cvt_pk_bf16_f32 v124, v100, v101
	v_cvt_pk_bf16_f32 v125, v104, v105
	v_cvt_pk_bf16_f32 v126, v106, v107
	v_cvt_pk_bf16_f32 v127, v110, v111
	global_store_dwordx4 v[96:97], v[124:127], off
	v_lshlrev_b32_e32 v108, 16, v24
	v_and_b32_e32 v109, 0xffff0000, v24
	v_lshlrev_b32_e32 v112, 16, v25
	v_and_b32_e32 v113, 0xffff0000, v25
	v_lshlrev_b32_e32 v114, 16, v26
	v_and_b32_e32 v115, 0xffff0000, v26
	v_lshlrev_b32_e32 v122, 16, v27
	v_and_b32_e32 v123, 0xffff0000, v27
	v_pk_fma_f32 v[100:101], v[100:101], v[28:29], v[108:109]
	v_pk_fma_f32 v[104:105], v[104:105], v[30:31], v[112:113]
	v_pk_fma_f32 v[106:107], v[106:107], v[32:33], v[114:115]
	v_pk_fma_f32 v[110:111], v[110:111], v[34:35], v[122:123]
	global_load_dwordx4 v[24:27], v[98:99], off
	global_load_dwordx4 v[28:31], v[102:103], off
	global_load_dwordx4 v[32:35], v[102:103], off offset:32
	v_lshl_add_u64 v[98:99], v[98:99], 0, s[10:11]
	v_lshl_add_u64 v[102:103], v[102:103], 0, s[12:13]
	v_lshl_add_u64 v[96:97], v[96:97], 0, s[10:11]
	s_waitcnt vmcnt(28)
	v_cvt_pk_bf16_f32 v124, v100, v101
	v_cvt_pk_bf16_f32 v125, v104, v105
	v_cvt_pk_bf16_f32 v126, v106, v107
	v_cvt_pk_bf16_f32 v127, v110, v111
	global_store_dwordx4 v[96:97], v[124:127], off
	v_lshlrev_b32_e32 v108, 16, v36
	v_and_b32_e32 v109, 0xffff0000, v36
	v_lshlrev_b32_e32 v112, 16, v37
	v_and_b32_e32 v113, 0xffff0000, v37
	v_lshlrev_b32_e32 v114, 16, v38
	v_and_b32_e32 v115, 0xffff0000, v38
	v_lshlrev_b32_e32 v122, 16, v39
	v_and_b32_e32 v123, 0xffff0000, v39
	v_pk_fma_f32 v[100:101], v[100:101], v[40:41], v[108:109]
	v_pk_fma_f32 v[104:105], v[104:105], v[42:43], v[112:113]
	v_pk_fma_f32 v[106:107], v[106:107], v[44:45], v[114:115]
	v_pk_fma_f32 v[110:111], v[110:111], v[46:47], v[122:123]
	global_load_dwordx4 v[36:39], v[98:99], off
	global_load_dwordx4 v[40:43], v[102:103], off
	global_load_dwordx4 v[44:47], v[102:103], off offset:32
	v_lshl_add_u64 v[98:99], v[98:99], 0, s[10:11]
	v_lshl_add_u64 v[102:103], v[102:103], 0, s[12:13]
	v_lshl_add_u64 v[96:97], v[96:97], 0, s[10:11]
	s_waitcnt vmcnt(28)
	v_cvt_pk_bf16_f32 v124, v100, v101
	v_cvt_pk_bf16_f32 v125, v104, v105
	v_cvt_pk_bf16_f32 v126, v106, v107
	v_cvt_pk_bf16_f32 v127, v110, v111
	global_store_dwordx4 v[96:97], v[124:127], off
	v_lshlrev_b32_e32 v108, 16, v48
	v_and_b32_e32 v109, 0xffff0000, v48
	v_lshlrev_b32_e32 v112, 16, v49
	v_and_b32_e32 v113, 0xffff0000, v49
	v_lshlrev_b32_e32 v114, 16, v50
	v_and_b32_e32 v115, 0xffff0000, v50
	v_lshlrev_b32_e32 v122, 16, v51
	v_and_b32_e32 v123, 0xffff0000, v51
	v_pk_fma_f32 v[100:101], v[100:101], v[52:53], v[108:109]
	v_pk_fma_f32 v[104:105], v[104:105], v[54:55], v[112:113]
	v_pk_fma_f32 v[106:107], v[106:107], v[56:57], v[114:115]
	v_pk_fma_f32 v[110:111], v[110:111], v[58:59], v[122:123]
	global_load_dwordx4 v[48:51], v[98:99], off
	global_load_dwordx4 v[52:55], v[102:103], off
	global_load_dwordx4 v[56:59], v[102:103], off offset:32
	v_lshl_add_u64 v[98:99], v[98:99], 0, s[10:11]
	v_lshl_add_u64 v[102:103], v[102:103], 0, s[12:13]
	v_lshl_add_u64 v[96:97], v[96:97], 0, s[10:11]
	s_waitcnt vmcnt(28)
	v_cvt_pk_bf16_f32 v124, v100, v101
	v_cvt_pk_bf16_f32 v125, v104, v105
	v_cvt_pk_bf16_f32 v126, v106, v107
	v_cvt_pk_bf16_f32 v127, v110, v111
	global_store_dwordx4 v[96:97], v[124:127], off
	v_lshlrev_b32_e32 v108, 16, v60
	v_and_b32_e32 v109, 0xffff0000, v60
	v_lshlrev_b32_e32 v112, 16, v61
	v_and_b32_e32 v113, 0xffff0000, v61
	v_lshlrev_b32_e32 v114, 16, v62
	v_and_b32_e32 v115, 0xffff0000, v62
	v_lshlrev_b32_e32 v122, 16, v63
	v_and_b32_e32 v123, 0xffff0000, v63
	v_pk_fma_f32 v[100:101], v[100:101], v[64:65], v[108:109]
	v_pk_fma_f32 v[104:105], v[104:105], v[66:67], v[112:113]
	v_pk_fma_f32 v[106:107], v[106:107], v[68:69], v[114:115]
	v_pk_fma_f32 v[110:111], v[110:111], v[70:71], v[122:123]
	global_load_dwordx4 v[60:63], v[98:99], off
	global_load_dwordx4 v[64:67], v[102:103], off
	global_load_dwordx4 v[68:71], v[102:103], off offset:32
	v_lshl_add_u64 v[98:99], v[98:99], 0, s[10:11]
	v_lshl_add_u64 v[102:103], v[102:103], 0, s[12:13]
	v_lshl_add_u64 v[96:97], v[96:97], 0, s[10:11]
	s_waitcnt vmcnt(28)
	v_cvt_pk_bf16_f32 v124, v100, v101
	v_cvt_pk_bf16_f32 v125, v104, v105
	v_cvt_pk_bf16_f32 v126, v106, v107
	v_cvt_pk_bf16_f32 v127, v110, v111
	global_store_dwordx4 v[96:97], v[124:127], off
	v_lshlrev_b32_e32 v108, 16, v72
	v_and_b32_e32 v109, 0xffff0000, v72
	v_lshlrev_b32_e32 v112, 16, v73
	v_and_b32_e32 v113, 0xffff0000, v73
	v_lshlrev_b32_e32 v114, 16, v74
	v_and_b32_e32 v115, 0xffff0000, v74
	v_lshlrev_b32_e32 v122, 16, v75
	v_and_b32_e32 v123, 0xffff0000, v75
	v_pk_fma_f32 v[100:101], v[100:101], v[76:77], v[108:109]
	v_pk_fma_f32 v[104:105], v[104:105], v[78:79], v[112:113]
	v_pk_fma_f32 v[106:107], v[106:107], v[80:81], v[114:115]
	v_pk_fma_f32 v[110:111], v[110:111], v[82:83], v[122:123]
	global_load_dwordx4 v[72:75], v[98:99], off
	global_load_dwordx4 v[76:79], v[102:103], off
	global_load_dwordx4 v[80:83], v[102:103], off offset:32
	v_lshl_add_u64 v[98:99], v[98:99], 0, s[10:11]
	v_lshl_add_u64 v[102:103], v[102:103], 0, s[12:13]
	v_lshl_add_u64 v[96:97], v[96:97], 0, s[10:11]
	s_waitcnt vmcnt(28)
	v_cvt_pk_bf16_f32 v124, v100, v101
	v_cvt_pk_bf16_f32 v125, v104, v105
	v_cvt_pk_bf16_f32 v126, v106, v107
	v_cvt_pk_bf16_f32 v127, v110, v111
	global_store_dwordx4 v[96:97], v[124:127], off
	v_lshlrev_b32_e32 v108, 16, v84
	v_and_b32_e32 v109, 0xffff0000, v84
	v_lshlrev_b32_e32 v112, 16, v85
	v_and_b32_e32 v113, 0xffff0000, v85
	v_lshlrev_b32_e32 v114, 16, v86
	v_and_b32_e32 v115, 0xffff0000, v86
	v_lshlrev_b32_e32 v122, 16, v87
	v_and_b32_e32 v123, 0xffff0000, v87
	v_pk_fma_f32 v[100:101], v[100:101], v[88:89], v[108:109]
	v_pk_fma_f32 v[104:105], v[104:105], v[90:91], v[112:113]
	v_pk_fma_f32 v[106:107], v[106:107], v[118:119], v[114:115]
	v_pk_fma_f32 v[110:111], v[110:111], v[120:121], v[122:123]
	global_load_dwordx4 v[84:87], v[98:99], off
	global_load_dwordx4 v[88:91], v[102:103], off
	global_load_dwordx4 v[118:121], v[102:103], off offset:32
	v_lshl_add_u64 v[98:99], v[98:99], 0, s[10:11]
	v_lshl_add_u64 v[102:103], v[102:103], 0, s[12:13]
	v_lshl_add_u64 v[96:97], v[96:97], 0, s[10:11]
	s_add_i32 s5, s5, 1
	s_cmp_lt_u32 s5, 15
	s_cbranch_scc1 .Lg2_loop
	s_waitcnt vmcnt(28)
	v_cvt_pk_bf16_f32 v124, v100, v101
	v_cvt_pk_bf16_f32 v125, v104, v105
	v_cvt_pk_bf16_f32 v126, v106, v107
	v_cvt_pk_bf16_f32 v127, v110, v111
	global_store_dwordx4 v[96:97], v[124:127], off
	v_lshlrev_b32_e32 v108, 16, v0
	v_and_b32_e32 v109, 0xffff0000, v0
	v_lshlrev_b32_e32 v112, 16, v1
	v_and_b32_e32 v113, 0xffff0000, v1
	v_lshlrev_b32_e32 v114, 16, v2
	v_and_b32_e32 v115, 0xffff0000, v2
	v_lshlrev_b32_e32 v122, 16, v3
	v_and_b32_e32 v123, 0xffff0000, v3
	v_pk_fma_f32 v[100:101], v[100:101], v[4:5], v[108:109]
	v_pk_fma_f32 v[104:105], v[104:105], v[6:7], v[112:113]
	v_pk_fma_f32 v[106:107], v[106:107], v[8:9], v[114:115]
	v_pk_fma_f32 v[110:111], v[110:111], v[10:11], v[122:123]
	v_lshl_add_u64 v[96:97], v[96:97], 0, s[10:11]
	s_waitcnt vmcnt(25)
	v_cvt_pk_bf16_f32 v124, v100, v101
	v_cvt_pk_bf16_f32 v125, v104, v105
	v_cvt_pk_bf16_f32 v126, v106, v107
	v_cvt_pk_bf16_f32 v127, v110, v111
	global_store_dwordx4 v[96:97], v[124:127], off
	v_lshlrev_b32_e32 v108, 16, v12
	v_and_b32_e32 v109, 0xffff0000, v12
	v_lshlrev_b32_e32 v112, 16, v13
	v_and_b32_e32 v113, 0xffff0000, v13
	v_lshlrev_b32_e32 v114, 16, v14
	v_and_b32_e32 v115, 0xffff0000, v14
	v_lshlrev_b32_e32 v122, 16, v15
	v_and_b32_e32 v123, 0xffff0000, v15
	v_pk_fma_f32 v[100:101], v[100:101], v[16:17], v[108:109]
	v_pk_fma_f32 v[104:105], v[104:105], v[18:19], v[112:113]
	v_pk_fma_f32 v[106:107], v[106:107], v[20:21], v[114:115]
	v_pk_fma_f32 v[110:111], v[110:111], v[22:23], v[122:123]
	v_lshl_add_u64 v[96:97], v[96:97], 0, s[10:11]
	s_waitcnt vmcnt(22)
	v_cvt_pk_bf16_f32 v124, v100, v101
	v_cvt_pk_bf16_f32 v125, v104, v105
	v_cvt_pk_bf16_f32 v126, v106, v107
	v_cvt_pk_bf16_f32 v127, v110, v111
	global_store_dwordx4 v[96:97], v[124:127], off
	v_lshlrev_b32_e32 v108, 16, v24
	v_and_b32_e32 v109, 0xffff0000, v24
	v_lshlrev_b32_e32 v112, 16, v25
	v_and_b32_e32 v113, 0xffff0000, v25
	v_lshlrev_b32_e32 v114, 16, v26
	v_and_b32_e32 v115, 0xffff0000, v26
	v_lshlrev_b32_e32 v122, 16, v27
	v_and_b32_e32 v123, 0xffff0000, v27
	v_pk_fma_f32 v[100:101], v[100:101], v[28:29], v[108:109]
	v_pk_fma_f32 v[104:105], v[104:105], v[30:31], v[112:113]
	v_pk_fma_f32 v[106:107], v[106:107], v[32:33], v[114:115]
	v_pk_fma_f32 v[110:111], v[110:111], v[34:35], v[122:123]
	v_lshl_add_u64 v[96:97], v[96:97], 0, s[10:11]
	s_waitcnt vmcnt(19)
	v_cvt_pk_bf16_f32 v124, v100, v101
	v_cvt_pk_bf16_f32 v125, v104, v105
	v_cvt_pk_bf16_f32 v126, v106, v107
	v_cvt_pk_bf16_f32 v127, v110, v111
	global_store_dwordx4 v[96:97], v[124:127], off
	v_lshlrev_b32_e32 v108, 16, v36
	v_and_b32_e32 v109, 0xffff0000, v36
	v_lshlrev_b32_e32 v112, 16, v37
	v_and_b32_e32 v113, 0xffff0000, v37
	v_lshlrev_b32_e32 v114, 16, v38
	v_and_b32_e32 v115, 0xffff0000, v38
	v_lshlrev_b32_e32 v122, 16, v39
	v_and_b32_e32 v123, 0xffff0000, v39
	v_pk_fma_f32 v[100:101], v[100:101], v[40:41], v[108:109]
	v_pk_fma_f32 v[104:105], v[104:105], v[42:43], v[112:113]
	v_pk_fma_f32 v[106:107], v[106:107], v[44:45], v[114:115]
	v_pk_fma_f32 v[110:111], v[110:111], v[46:47], v[122:123]
	v_lshl_add_u64 v[96:97], v[96:97], 0, s[10:11]
	s_waitcnt vmcnt(16)
	v_cvt_pk_bf16_f32 v124, v100, v101
	v_cvt_pk_bf16_f32 v125, v104, v105
	v_cvt_pk_bf16_f32 v126, v106, v107
	v_cvt_pk_bf16_f32 v127, v110, v111
	global_store_dwordx4 v[96:97], v[124:127], off
	v_lshlrev_b32_e32 v108, 16, v48
	v_and_b32_e32 v109, 0xffff0000, v48
	v_lshlrev_b32_e32 v112, 16, v49
	v_and_b32_e32 v113, 0xffff0000, v49
	v_lshlrev_b32_e32 v114, 16, v50
	v_and_b32_e32 v115, 0xffff0000, v50
	v_lshlrev_b32_e32 v122, 16, v51
	v_and_b32_e32 v123, 0xffff0000, v51
	v_pk_fma_f32 v[100:101], v[100:101], v[52:53], v[108:109]
	v_pk_fma_f32 v[104:105], v[104:105], v[54:55], v[112:113]
	v_pk_fma_f32 v[106:107], v[106:107], v[56:57], v[114:115]
	v_pk_fma_f32 v[110:111], v[110:111], v[58:59], v[122:123]
	v_lshl_add_u64 v[96:97], v[96:97], 0, s[10:11]
	s_waitcnt vmcnt(13)
	v_cvt_pk_bf16_f32 v124, v100, v101
	v_cvt_pk_bf16_f32 v125, v104, v105
	v_cvt_pk_bf16_f32 v126, v106, v107
	v_cvt_pk_bf16_f32 v127, v110, v111
	global_store_dwordx4 v[96:97], v[124:127], off
	v_lshlrev_b32_e32 v108, 16, v60
	v_and_b32_e32 v109, 0xffff0000, v60
	v_lshlrev_b32_e32 v112, 16, v61
	v_and_b32_e32 v113, 0xffff0000, v61
	v_lshlrev_b32_e32 v114, 16, v62
	v_and_b32_e32 v115, 0xffff0000, v62
	v_lshlrev_b32_e32 v122, 16, v63
	v_and_b32_e32 v123, 0xffff0000, v63
	v_pk_fma_f32 v[100:101], v[100:101], v[64:65], v[108:109]
	v_pk_fma_f32 v[104:105], v[104:105], v[66:67], v[112:113]
	v_pk_fma_f32 v[106:107], v[106:107], v[68:69], v[114:115]
	v_pk_fma_f32 v[110:111], v[110:111], v[70:71], v[122:123]
	v_lshl_add_u64 v[96:97], v[96:97], 0, s[10:11]
	s_waitcnt vmcnt(10)
	v_cvt_pk_bf16_f32 v124, v100, v101
	v_cvt_pk_bf16_f32 v125, v104, v105
	v_cvt_pk_bf16_f32 v126, v106, v107
	v_cvt_pk_bf16_f32 v127, v110, v111
	global_store_dwordx4 v[96:97], v[124:127], off
	v_lshlrev_b32_e32 v108, 16, v72
	v_and_b32_e32 v109, 0xffff0000, v72
	v_lshlrev_b32_e32 v112, 16, v73
	v_and_b32_e32 v113, 0xffff0000, v73
	v_lshlrev_b32_e32 v114, 16, v74
	v_and_b32_e32 v115, 0xffff0000, v74
	v_lshlrev_b32_e32 v122, 16, v75
	v_and_b32_e32 v123, 0xffff0000, v75
	v_pk_fma_f32 v[100:101], v[100:101], v[76:77], v[108:109]
	v_pk_fma_f32 v[104:105], v[104:105], v[78:79], v[112:113]
	v_pk_fma_f32 v[106:107], v[106:107], v[80:81], v[114:115]
	v_pk_fma_f32 v[110:111], v[110:111], v[82:83], v[122:123]
	v_lshl_add_u64 v[96:97], v[96:97], 0, s[10:11]
	s_waitcnt vmcnt(7)
	v_cvt_pk_bf16_f32 v124, v100, v101
	v_cvt_pk_bf16_f32 v125, v104, v105
	v_cvt_pk_bf16_f32 v126, v106, v107
	v_cvt_pk_bf16_f32 v127, v110, v111
	global_store_dwordx4 v[96:97], v[124:127], off
	v_lshlrev_b32_e32 v108, 16, v84
	v_and_b32_e32 v109, 0xffff0000, v84
	v_lshlrev_b32_e32 v112, 16, v85
	v_and_b32_e32 v113, 0xffff0000, v85
	v_lshlrev_b32_e32 v114, 16, v86
	v_and_b32_e32 v115, 0xffff0000, v86
	v_lshlrev_b32_e32 v122, 16, v87
	v_and_b32_e32 v123, 0xffff0000, v87
	v_pk_fma_f32 v[100:101], v[100:101], v[88:89], v[108:109]
	v_pk_fma_f32 v[104:105], v[104:105], v[90:91], v[112:113]
	v_pk_fma_f32 v[106:107], v[106:107], v[118:119], v[114:115]
	v_pk_fma_f32 v[110:111], v[110:111], v[120:121], v[122:123]
	v_lshl_add_u64 v[96:97], v[96:97], 0, s[10:11]
	v_add_u32_e32 v116, s82, v116
	s_mov_b32 s5, 0xffff
	v_cmp_lt_i32_e32 vcc, s5, v116
	v_readlane_b32 s5, v245, 8
	s_or_b64 s[8:9], vcc, s[8:9]
	s_nop 0
	v_add_u32_e32 v117, s5, v117
	s_andn2_b64 exec, exec, s[8:9]
	s_cbranch_execnz .LBB0_140
